# RET units: two barriers per key tile with waves 4-7 one barrier behind (stagger), DMA look-ahead 2; plus barrier relocation and static priority
# speedup vs baseline: 1.0010x; 1.0010x over previous
; #define QLOOP2(qi_, r2_, n_, ...) for (;;) { if (tid == 0) s_item = (int)atomicAdd(ctr + 64 * (qi_) + 32 * (r2_), 1u); __syncthreads(); const int item = s_item; __syncthreads(); if (item >= (n_)) break; __VA_ARGS__ }
; template <int PHM, int MIXM>
; __global__ void __launch_bounds__(512, 2) mega(Args Aval) {
;     ...
;             for (int r2 = 0; r2 < ((PROBE_DUP & 16) ? 2 : 1); ++r2) if (MIXM & 1) QLOOP2(0, r2, 256, { const int L = 15 - (item >> 4), r = item & 15; flash_unit<0>(A, l, r >> 2, r & 3, L, lds); })
;             for (int r2 = 0; r2 < ((PROBE_DUP & 32) ? 2 : 1); ++r2) if (MIXM & 2) QLOOP2(1, r2, 256, { const int L = 15 - (item >> 4), r = item & 15; flash_unit<2>(A, l, r >> 2, r & 3, L, lds); })
.LBB0_759:
	v_readfirstlane_b32 s8, v238
	s_cmp_ge_u32 s8, 0x100
	s_cbranch_scc1 .Lret_nobal
	s_barrier

; template <int MODE>
; __device__ __forceinline__ void flash_unit(ArgsP A, int l, int b, int h, int qb, unsigned char* lds) {
;     ...
;         const bf16_t* qp = PROJ + (size_t)qrow * INWP + C_RQ + 64 * h + 8 * hh;
; #pragma unroll
;         for (int s = 0; s < NS; ++s) qf[s] = __builtin_bit_cast(bf16x8, *(const u32x4*)(qp + 16 * s));
;     }
;     int posq = 0, qmin = 0; float bfar = 0.f;
;     if (MODE == 1) {
;         const int* pos = (const int*)A->in[2];
;         if (tid < 129) { int n = tid; int bucket;
;             if (n < 16) bucket = n; else { const float nf = (float)n; int lg = 16 + (int)(logf(nf / 16.f) / 2.0794415416798357f * 16.f); bucket = lg < 31 ? lg : 31; }
;             if (tid == 128) bucket = 31;
;             btab[tid] = A->in[3][bucket * 4 + h] * LOG2E; }
;         posq = pos[qrow];
;         int mn = posq;
; #pragma unroll
;         for (int o = 1; o < 64; o <<= 1) { const int other = __shfl_xor(mn, o); mn = other < mn ? other : mn; }
;         qmin = mn;
;     }
;     float lg2 = 0.f;
;     if (MODE == 2) lg2 = log2f(1.f - exp2f(-5.f - (float)h));
;     const unsigned lds0 = (unsigned)(uintptr_t)lds;
;     int kbase[4];
; #pragma unroll
;     for (int bsel = 0; bsel < 4; ++bsel) { const int ch = 2 * bsel + hh + (MODE == 1 ? 8 * map : 0), xr = (MODE == 1) ? (q32 & 15) : ((q32 >> 1) & 7); kbase[bsel] = (q32 * KCH + (ch ^ xr)) * 16; }
;     auto dma_tile = [&](int t) {
;         const int kr0 = rowbase + 64 * t;
;         const int slot = t % NBUF; const unsigned kb_ = lds0 + slot * KBYTES, vb_ = lds0 + NBUF * KBYTES + slot * VBYTES;
; #pragma unroll
;         for (int i = 0; i < NKI; ++i) { const int piece = wave + 8 * i, p = 64 * piece + lane, key = p / KCH, cs = p % KCH;
;             const int ch = cs ^ (MODE == 1 ? (key & 15) : ((key >> 1) & 7)); const bf16_t* src;
;             if (MODE == 0) src = (ch < 16) ? KVM + (size_t)(kr0 + key) * 1024 + 256 * h + 8 * ch : PROJ + (size_t)(kr0 + key) * INWP + C_KR + 8 * (ch - 16);
;             else if (MODE == 1) src = PROJ + (size_t)(kr0 + key) * INWP + C_DK + 128 * h + 8 * ch;
;             else src = PROJ + (size_t)(kr0 + key) * INWP + C_RK + 64 * h + 8 * ch;
;             glds16(src, (unsigned)__builtin_amdgcn_readfirstlane(kb_ + piece * 1024)); }
; #pragma unroll
.Lprio_skip_ret:
	v_mov_b32_e32 v10, v238
	s_load_dwordx2 s[2:3], s[26:27], 0x148
	v_readfirstlane_b32 s15, v10
	s_and_b32 s4, s5, 3
	s_ashr_i32 s16, s15, 6
	v_and_b32_e32 v4, 31, v10
	s_waitcnt lgkmcnt(0)
	s_add_u32 s6, s2, 0x18f90000
	s_addc_u32 s7, s3, 0
	s_lshl_b32 s8, s5, 10
	s_lshl_b32 s5, s5, 4
	s_and_b32 s17, s8, 0x3000
	s_and_b32 s5, s5, 0xffffff00
	s_lshl_b32 s8, s16, 5
	s_sub_i32 s8, s8, s5
	s_add_i32 s13, s8, 0xf00
	v_or_b32_e32 v164, s13, v4
	v_add_u32_e32 v160, s17, v164
	v_mov_b64_e32 v[0:1], s[6:7]
	v_bfe_u32 v11, v10, 5, 1
	v_mad_i64_i32 v[162:163], s[8:9], v160, s35, v[0:1]
	s_lshl_b32 s18, s4, 7
	v_lshl_add_u64 v[2:3], v[162:163], 0, s[18:19]
	v_lshlrev_b32_e32 v176, 4, v11
	v_lshl_add_u64 v[2:3], v[2:3], 0, v[176:177]
	global_load_dwordx4 v[144:147], v[2:3], off offset:2432
	global_load_dwordx4 v[148:151], v[2:3], off offset:2464
	global_load_dwordx4 v[152:155], v[2:3], off offset:2496
	global_load_dwordx4 v[156:159], v[2:3], off offset:2528
	v_cvt_f32_ubyte0_e32 v5, s4
	v_sub_f32_e32 v5, 0xc0a00000, v5
	s_mov_b32 s8, 0xc2fc0000
	v_cmp_gt_f32_e32 vcc, s8, v5
	v_mov_b32_e32 v9, 0x42800000
	v_lshrrev_b32_e32 v7, 1, v10
	v_cndmask_b32_e32 v9, 0, v9, vcc
	v_add_f32_e32 v5, v5, v9
	v_exp_f32_e32 v5, v5
	s_sub_i32 s5, 0x1000, s5
	v_lshlrev_b32_e32 v192, 7, v4
	v_bitop3_b32 v4, v11, v7, 7 bitop3:0x78
	v_mov_b32_e32 v13, s15
	s_movk_i32 s8, 0xffc0
	s_lshr_b32 s12, s5, 6
	v_lshlrev_b32_e32 v193, 4, v4
	v_bfi_b32 v4, s8, v13, v10
	s_and_b64 s[8:9], vcc, exec
	s_cselect_b32 s5, 0xffffffc0, 0
	s_ashr_i32 s8, s13, 31
	v_ldexp_f32 v5, v5, s5
	s_lshr_b32 s5, s8, 26
	s_add_i32 s5, s5, s13
	v_sub_f32_e32 v5, 1.0, v5
	s_add_i32 s5, s5, 31
	s_mov_b32 s8, 0x800000
	v_cmp_gt_f32_e32 vcc, s8, v5
	s_ashr_i32 s13, s5, 6
	s_and_b64 s[8:9], vcc, exec
	s_cselect_b32 s5, 32, 0
	v_ldexp_f32 v5, v5, s5
	v_bfe_u32 v8, v10, 1, 3
	v_log_f32_e32 v5, v5
	v_bitop3_b32 v7, v11, v8, 2 bitop3:0x36
	v_lshlrev_b32_e32 v194, 4, v7
	v_mov_b32_e32 v7, 0x42000000
	s_ashr_i32 s8, s15, 31
	v_bitop3_b32 v12, v11, v8, 4 bitop3:0x36
	v_bitop3_b32 v8, v11, v8, 6 bitop3:0x36
	v_cndmask_b32_e32 v7, 0, v7, vcc
	s_lshr_b32 s5, s8, 29
	v_mov_b32_e32 v2, v177
	v_mov_b32_e32 v3, v177
	v_lshlrev_b32_e32 v196, 4, v8
	v_add_u32_e32 v8, s5, v4
	v_sub_f32_e32 v197, v5, v7
	v_lshlrev_b32_e32 v195, 4, v12
	s_lshl_b32 s14, s16, 10
	v_ashrrev_i32_e32 v12, 3, v8
	v_and_b32_e32 v8, 0x1ffffff8, v8
	s_cmp_lg_u32 16, -1
	v_sub_u32_e32 v8, v4, v8
	v_lshrrev_b32_e32 v9, 1, v12
	v_and_b32_e32 v6, 63, v10
	s_cselect_b32 s20, 16, 0
	v_bitop3_b32 v8, v9, v8, 7 bitop3:0x6c
	s_movk_i32 s8, 0x60
	s_add_i32 s16, s16, 8
	v_lshlrev_b32_e32 v166, 3, v8
	v_add_u32_e32 v14, s17, v12
	v_ashrrev_i32_e32 v167, 31, v166
	s_ashr_i32 s5, s15, 4
	s_and_b32 s21, s5, -8
	s_lshl_b32 s5, s16, 2
	s_add_i32 s15, s14, s20
	s_and_b32 s22, s5, -8
	s_waitcnt vmcnt(3)
	s_waitcnt vmcnt(2)
	s_waitcnt vmcnt(1)
	s_waitcnt vmcnt(0)
	s_nop 0
	v_lshlrev_b32_e32 v2, 3, v10
	v_and_b32_e32 v13, 24, v2
	v_and_or_b32 v2, v4, s8, v13
	v_lshl_or_b32 v4, s16, 6, v6
	v_and_or_b32 v16, v4, s8, v13
	v_mad_i64_i32 v[4:5], s[8:9], v14, s35, v[0:1]
	v_lshl_add_u64 v[4:5], v[4:5], 0, s[18:19]
	v_lshlrev_b64 v[6:7], 1, v[166:167]
	v_bfe_u32 v3, v10, 2, 3
	v_lshl_add_u64 v[4:5], v[4:5], 0, v[6:7]
	v_lshl_add_u64 v[4:5], v[4:5], 0, s[88:89]
	v_or_b32_e32 v8, s17, v3
	s_barrier
; template <int MODE>
; __device__ __forceinline__ void flash_unit(ArgsP A, int l, int b, int h, int qb, unsigned char* lds) {
;     ...
;     auto dma_tile = [&](int t) {
;         const int kr0 = rowbase + 64 * t;
;         const int slot = t % NBUF; const unsigned kb_ = lds0 + slot * KBYTES, vb_ = lds0 + NBUF * KBYTES + slot * VBYTES;
; #pragma unroll
;         for (int i = 0; i < NKI; ++i) { const int piece = wave + 8 * i, p = 64 * piece + lane, key = p / KCH, cs = p % KCH;
;             const int ch = cs ^ (MODE == 1 ? (key & 15) : ((key >> 1) & 7)); const bf16_t* src;
;             if (MODE == 0) src = (ch < 16) ? KVM + (size_t)(kr0 + key) * 1024 + 256 * h + 8 * ch : PROJ + (size_t)(kr0 + key) * INWP + C_KR + 8 * (ch - 16);
;             else if (MODE == 1) src = PROJ + (size_t)(kr0 + key) * INWP + C_DK + 128 * h + 8 * ch;
;             else src = PROJ + (size_t)(kr0 + key) * INWP + C_RK + 64 * h + 8 * ch;
;             glds16(src, (unsigned)__builtin_amdgcn_readfirstlane(kb_ + piece * 1024)); }
; #pragma unroll
;         for (int i = 0; i < 2; ++i) { const int piece = wave + 8 * i, p = 64 * piece + lane, st = p >> 5, key = 8 * (st >> 2) + ((p & 31) >> 2), col = 32 * (st & 3) + 8 * (p & 3); const bf16_t* src;
;             if (MODE == 0) src = KVM + (size_t)(kr0 + key) * 1024 + 256 * h + 128 + col;
;             else if (MODE == 1) src = PROJ + (size_t)(kr0 + key) * INWP + C_DV + 128 * h + col;
;             else src = PROJ + (size_t)(kr0 + key) * INWP + C_RV + 128 * h + col;
;             glds16(src, (unsigned)__builtin_amdgcn_readfirstlane(vb_ + piece * 1024)); }
;         if (MODE == 1) glds4((const int*)A->in[2] + rowbase + 64 * t + lane, (unsigned)__builtin_amdgcn_readfirstlane(lds0 + OFF_EXTRA + slot * 256));
;     };
;     f32x16 oacc[4];
; #pragma unroll
;     for (int c = 0; c < 4; ++c)
; #pragma unroll
;         for (int i = 0; i < 16; ++i) oacc[c][i] = 0.f;
;     float m_run = -INFINITY, l_run = 0.f;
; #pragma unroll
;     for (int s_ = 0; s_ < NS; ++s_) asm volatile("" : "+v"(qf[s_]));
;     asm volatile("" : "+v"(posq), "+v"(qmin), "+v"(lg2));
;     __syncthreads();
; #pragma unroll
;     for (int i = 0; i < NBUF - 1; ++i) if (i < ntile) dma_tile(i);
	s_mov_b32 s5, m0
	s_mov_b32 m0, s15
	s_nop 0
	global_load_lds_dwordx4 v[4:5], off
	s_mov_b32 m0, s5
	v_add_u32_e32 v4, s21, v8
	v_mad_i64_i32 v[4:5], s[8:9], v4, s35, v[0:1]
	s_lshl_b32 s8, s4, 8
	s_mov_b32 s9, s19
	v_lshl_add_u64 v[4:5], v[4:5], 0, s[8:9]
	v_lshlrev_b32_e32 v176, 1, v2
	v_lshl_add_u64 v[4:5], v[4:5], 0, v[176:177]
	v_lshl_add_u64 v[4:5], v[4:5], 0, s[90:91]
	s_add_i32 s23, s20, 0x8000
	s_add_i32 s4, s14, s23
	s_mov_b32 s5, m0
	s_mov_b32 m0, s4
	s_nop 0
	global_load_lds_dwordx4 v[4:5], off
	s_mov_b32 m0, s5
	v_add_u32_e32 v4, s22, v8
	v_mad_i64_i32 v[4:5], s[4:5], v4, s35, v[0:1]
	v_lshl_add_u64 v[4:5], v[4:5], 0, s[8:9]
	v_lshlrev_b32_e32 v8, 1, v16
	v_mov_b32_e32 v9, v177
	s_lshl_b32 s16, s16, 10
	v_lshl_add_u64 v[4:5], v[4:5], 0, v[8:9]
	v_lshl_add_u64 v[4:5], v[4:5], 0, s[90:91]
	s_add_i32 s4, s16, s23
	s_or_b32 s23, s17, 64
	s_mov_b32 s5, m0
	s_mov_b32 m0, s4
	s_nop 0
	global_load_lds_dwordx4 v[4:5], off
	s_mov_b32 m0, s5
	v_add_u32_e32 v4, s23, v12
	v_mad_i64_i32 v[4:5], s[4:5], v4, s35, v[0:1]
	v_lshl_add_u64 v[4:5], v[4:5], 0, s[18:19]
	v_lshl_add_u64 v[4:5], v[4:5], 0, v[6:7]
	v_lshl_add_u64 v[4:5], v[4:5], 0, s[88:89]
	v_or_b32_e32 v15, s23, v3
	s_add_i32 s4, s15, 0x2000
	s_mov_b32 s5, m0
	s_mov_b32 m0, s4
	s_nop 0
	global_load_lds_dwordx4 v[4:5], off
	s_mov_b32 m0, s5
	v_add_u32_e32 v4, s21, v15
	v_mad_i64_i32 v[4:5], s[4:5], v4, s35, v[0:1]
	v_lshl_add_u64 v[4:5], v[4:5], 0, s[8:9]
	v_lshl_add_u64 v[4:5], v[4:5], 0, v[176:177]
	v_lshl_add_u64 v[4:5], v[4:5], 0, s[90:91]
	s_add_i32 s23, s20, 0xc000
	s_add_i32 s4, s14, s23
	s_mov_b32 s5, m0
	s_mov_b32 m0, s4
	s_nop 0
	global_load_lds_dwordx4 v[4:5], off
	s_mov_b32 m0, s5
	v_add_u32_e32 v4, s22, v15
	v_mad_i64_i32 v[4:5], s[4:5], v4, s35, v[0:1]
	v_lshl_add_u64 v[4:5], v[4:5], 0, s[8:9]
	v_lshl_add_u64 v[4:5], v[4:5], 0, v[8:9]
	v_lshl_add_u64 v[4:5], v[4:5], 0, s[90:91]
	s_add_i32 s4, s16, s23
	s_or_b32 s23, s17, 0x80
	s_mov_b32 s5, m0
	s_mov_b32 m0, s4
	s_nop 0
	global_load_lds_dwordx4 v[4:5], off
	s_mov_b32 m0, s5
	v_add_u32_e32 v4, s23, v12
	v_mad_i64_i32 v[4:5], s[4:5], v4, s35, v[0:1]
	v_lshl_add_u64 v[4:5], v[4:5], 0, s[18:19]
	v_lshl_add_u64 v[4:5], v[4:5], 0, v[6:7]
	v_lshl_add_u64 v[4:5], v[4:5], 0, s[88:89]
	v_or_b32_e32 v6, s23, v3
	s_add_i32 s4, s15, 0x4000
	s_mov_b32 s5, m0
	s_mov_b32 m0, s4
	s_nop 0
	s_nop 0
	s_mov_b32 m0, s5
	v_add_u32_e32 v4, s21, v6
	v_mad_i64_i32 v[4:5], s[4:5], v4, s35, v[0:1]
	v_lshl_add_u64 v[4:5], v[4:5], 0, s[8:9]
	v_lshl_add_u64 v[4:5], v[4:5], 0, v[176:177]
	v_lshl_add_u64 v[4:5], v[4:5], 0, s[90:91]
	s_add_i32 s20, s20, 0x10000
	s_add_i32 s4, s14, s20
	s_mov_b32 s5, m0
	s_mov_b32 m0, s4
	s_nop 0
	s_nop 0
	s_mov_b32 m0, s5
	v_add_u32_e32 v4, s22, v6
	v_mad_i64_i32 v[0:1], s[4:5], v4, s35, v[0:1]
	v_lshl_add_u64 v[0:1], v[0:1], 0, s[8:9]
	v_lshl_add_u64 v[0:1], v[0:1], 0, v[8:9]
	s_add_i32 s4, s16, s20
	v_lshl_add_u64 v[0:1], v[0:1], 0, s[90:91]
	s_mov_b32 s5, m0
	s_mov_b32 m0, s4
	s_nop 0
	s_nop 0
	s_mov_b32 m0, s5
	s_add_u32 s4, s6, s18
	v_lshlrev_b32_e32 v1, 4, v10
	s_addc_u32 s5, s7, 0
	v_lshlrev_b32_e32 v0, 8, v11
	v_and_b32_e32 v1, 0xc0, v1
	s_add_u32 s6, s6, s8
	v_add3_u32 v0, 16, v0, v1
	v_lshlrev_b32_e32 v1, 1, v10
	s_addc_u32 s7, s7, 0
	s_or_b32 s8, s17, 0x80
	v_and_b32_e32 v1, 32, v1
	s_add_i32 s9, s8, s22
	s_add_i32 s8, s8, s21
	v_add_u32_e32 v202, 0x80, v14
	v_mov_b32_e32 v14, v177
	v_mov_b32_e32 v15, v177
	v_lshlrev_b32_e32 v198, 2, v11
	v_add3_u32 v199, v0, v1, v13
	v_or_b32_e32 v200, s9, v3
	v_or_b32_e32 v201, s8, v3
	v_lshlrev_b32_e32 v176, 1, v2
	v_mov_b32_e32 v0, v177
	v_mov_b32_e32 v1, v177
	v_mov_b32_e32 v2, v177
	v_mov_b32_e32 v3, v177
	v_mov_b32_e32 v4, v177
	v_mov_b32_e32 v5, v177
	v_mov_b32_e32 v6, v177
	v_mov_b32_e32 v7, v177
	v_mov_b32_e32 v8, v177
	v_mov_b32_e32 v10, v177
	v_mov_b32_e32 v11, v177
	v_mov_b32_e32 v12, v177
	v_mov_b32_e32 v13, v177
	v_lshlrev_b32_e32 v168, 1, v16
	v_mov_b64_e32 v[30:31], v[14:15]
	v_mov_b64_e32 v[46:47], v[14:15]
	v_mov_b64_e32 v[62:63], v[14:15]
	s_mov_b32 s10, 0
	s_mov_b32 s11, -1
	v_ashrrev_i32_e32 v161, 31, v160
	v_mov_b32_e32 v165, v164
	v_mov_b32_e32 v64, v164
	v_mov_b32_e32 v65, v164
	v_mov_b32_e32 v66, v164
	v_mov_b32_e32 v67, v164
	v_mov_b32_e32 v68, v164
	v_mov_b32_e32 v69, v164
	v_mov_b32_e32 v70, v164
	v_mov_b32_e32 v71, v164
	v_mov_b32_e32 v72, v164
	v_mov_b32_e32 v73, v164
	v_mov_b32_e32 v74, v164
	v_mov_b32_e32 v75, v164
	s_add_i32 s17, s12, -2
	s_mov_b32 s24, 0
	v_mov_b32_e32 v203, v164
	v_mov_b32_e32 v76, v164
	v_mov_b32_e32 v77, v164
	v_mov_b32_e32 v78, v164
	v_mov_b32_e32 v79, v164
	v_mov_b64_e32 v[28:29], v[12:13]
	v_mov_b64_e32 v[26:27], v[10:11]
	v_mov_b64_e32 v[24:25], v[8:9]
	v_mov_b64_e32 v[22:23], v[6:7]
	v_mov_b64_e32 v[20:21], v[4:5]
	v_mov_b64_e32 v[18:19], v[2:3]
	v_mov_b64_e32 v[16:17], v[0:1]
	v_mov_b64_e32 v[44:45], v[12:13]
	v_mov_b64_e32 v[42:43], v[10:11]
	v_mov_b64_e32 v[40:41], v[8:9]
	v_mov_b64_e32 v[38:39], v[6:7]
	v_mov_b64_e32 v[36:37], v[4:5]
	v_mov_b64_e32 v[34:35], v[2:3]
	v_mov_b64_e32 v[32:33], v[0:1]
	v_mov_b64_e32 v[60:61], v[12:13]
	v_mov_b64_e32 v[58:59], v[10:11]
	v_mov_b64_e32 v[56:57], v[8:9]
	v_mov_b64_e32 v[54:55], v[6:7]
	v_mov_b64_e32 v[52:53], v[4:5]
	v_mov_b64_e32 v[50:51], v[2:3]
	v_mov_b64_e32 v[48:49], v[0:1]
	v_readfirstlane_b32 s8, v238
	s_cmp_lt_u32 s8, 0x100
	s_cbranch_scc1 .Lret_nooff
	s_waitcnt vmcnt(3) lgkmcnt(0)
	s_barrier

; template <int MODE>
; __device__ __forceinline__ void flash_unit(ArgsP A, int l, int b, int h, int qb, unsigned char* lds) {
;     ...
;     for (int t = 0; t < ntile; ++t) {
;         {
;             const int later = (ntile - 1 - t) < (NBUF - 2) ? (ntile - 1 - t) : (NBUF - 2);
;             if (later <= 0) asm volatile("s_waitcnt vmcnt(0) lgkmcnt(0)\n\ts_barrier" ::: "memory");
;             else if (later == 1) asm volatile("s_waitcnt vmcnt(%0) lgkmcnt(0)\n\ts_barrier" :: "n"(OPS) : "memory");
;             else asm volatile("s_waitcnt vmcnt(%0) lgkmcnt(0)\n\ts_barrier" :: "n"(2 * OPS) : "memory");
;         }
;         if (t + NBUF - 1 < ntile) dma_tile(t + NBUF - 1);
.LBB0_767:
	s_add_i32 s8, s24, 2
	s_cmp_lt_u32 s8, s12
	s_cbranch_scc1 .Lret_B3
	s_waitcnt vmcnt(0) lgkmcnt(0)
	s_barrier
	s_branch .Lret_Bd
.Lret_B3:
	s_waitcnt vmcnt(3) lgkmcnt(0)
	s_barrier

; template <int MODE>
; __device__ __forceinline__ void flash_unit(ArgsP A, int l, int b, int h, int qb, unsigned char* lds) {
;     ...
;     for (int t = 0; t < ntile; ++t) {
;         {
;             const int later = (ntile - 1 - t) < (NBUF - 2) ? (ntile - 1 - t) : (NBUF - 2);
;             if (later <= 0) asm volatile("s_waitcnt vmcnt(0) lgkmcnt(0)\n\ts_barrier" ::: "memory");
;             else if (later == 1) asm volatile("s_waitcnt vmcnt(%0) lgkmcnt(0)\n\ts_barrier" :: "n"(OPS) : "memory");
;             else asm volatile("s_waitcnt vmcnt(%0) lgkmcnt(0)\n\ts_barrier" :: "n"(2 * OPS) : "memory");
;         }
;         if (t + NBUF - 1 < ntile) dma_tile(t + NBUF - 1);
.LBB0_769:
	s_add_i32 s8, s24, 1
	s_cmp_lt_u32 s8, s12
	s_cbranch_scc1 .Lret_A3
	s_waitcnt vmcnt(0) lgkmcnt(0)
	s_barrier
	s_branch .LBB0_771

; template <int MODE>
; __device__ __forceinline__ void flash_unit(ArgsP A, int l, int b, int h, int qb, unsigned char* lds) {
;     ...
;         if (t + NBUF - 1 < ntile) dma_tile(t + NBUF - 1);
.LBB0_771:
	s_add_i32 s8, s24, 2
	s_cmp_ge_u32 s8, s12
	s_cbranch_scc0 .LBB0_779

; template <int MODE>
; __device__ __forceinline__ void flash_unit(ArgsP A, int l, int b, int h, int qb, unsigned char* lds) {
;     ...
;             const int later = (ntile - 1 - t) < (NBUF - 2) ? (ntile - 1 - t) : (NBUF - 2);
;             if (later <= 0) asm volatile("s_waitcnt vmcnt(0) lgkmcnt(0)\n\ts_barrier" ::: "memory");
;             else if (later == 1) asm volatile("s_waitcnt vmcnt(%0) lgkmcnt(0)\n\ts_barrier" :: "n"(OPS) : "memory");
;             else asm volatile("s_waitcnt vmcnt(%0) lgkmcnt(0)\n\ts_barrier" :: "n"(2 * OPS) : "memory");
;         }
;         if (t + NBUF - 1 < ntile) dma_tile(t + NBUF - 1);
.Lret_sB3:
	s_waitcnt vmcnt(3) lgkmcnt(0)
	s_barrier
	s_branch .LBB0_768
